# attn merge: CARRY row loaded once per wave (1 dwordx4) and redistributed through LDS instead of 8 scattered loads
# baseline (speedup 1.0000x reference)
; template <int DV>
; DI void attn_unit(const int wv, const Args& A, LAS unsigned char* lds, int b, int g, int qb, int dry) {
;     ...
;         bf16* Yb = (bf16*)A.out; const bf16* GMA = (const bf16*)(ws + WS_GMA);
; #pragma unroll
;         for (int mt = 0; mt < 2; ++mt)
; #pragma unroll
;             for (int v = 0; v < 4; ++v) {
;                 const size_t idx = tokrow * DM + head * 64 + mt * 32 + 8 * v + 4 * c.h;
;                 const u32x2 yr = *(const u32x2*)(Yb + idx), gm = *(const u32x2*)(GMA + idx), ct = *(const u32x2*)((const bf16*)(ws + WS_CT) + idx);
;                 const f32x4 cr = *(const f32x4*)((const float*)(ws + WS_CARRY) + ((size_t)b * 64 + (c.t >> 7)) * DM + head * 64 + mt * 32 + 8 * v + 4 * c.h);
.LBB0_789:
	s_waitcnt vmcnt(0)
	v_or_b32_e32 v0, v211, v154
	v_or_b32_e32 v164, v0, v164
	v_mad_u32_u24 v10, v154, 7, v164
	v_mov_b32_e32 v11, v165
	v_lshlrev_b64 v[10:11], 1, v[10:11]
	v_readlane_b32 s8, v254, 2
	v_readlane_b32 s9, v254, 3
	v_lshl_add_u64 v[4:5], s[64:65], 0, v[10:11]
	v_lshl_add_u64 v[6:7], s[66:67], 0, v[10:11]
	s_nop 0
	v_lshl_add_u64 v[0:1], s[8:9], 0, v[10:11]
	s_lshr_b32 s62, s91, 7
	s_lshl_b32 s6, s45, 18
	v_readlane_b32 s7, v254, 59
	s_nop 3
	s_add_u32 s8, s7, s6
	s_addc_u32 s9, s89, 0
	s_lshl_b64 s[6:7], s[62:63], 12
	s_add_u32 s6, s8, s6
	v_lshlrev_b32_e32 v8, 2, v211
	v_mov_b32_e32 v9, v2
	s_addc_u32 s7, s9, s7
	v_mov_b32_e32 v155, v2
	v_lshl_add_u64 v[8:9], s[6:7], 0, v[8:9]
	v_lshl_add_u64 v[12:13], v[154:155], 2, v[8:9]
	v_mbcnt_lo_u32_b32 v14, -1, 0
	v_mbcnt_hi_u32_b32 v14, -1, v14
	v_and_b32_e32 v15, -256, v211
	v_lshlrev_b32_e32 v15, 2, v15
	v_lshl_add_u32 v15, v14, 4, v15
	global_load_dwordx4 v[248:251], v15, s[6:7]
	s_lshl_b32 s8, s83, 7
	v_lshl_add_u32 v10, v14, 4, s8
	v_and_b32_e32 v11, 0xc0, v211
	v_lshlrev_b32_e32 v11, 2, v11
	v_lshl_add_u32 v11, v154, 2, v11
	v_add_u32_e32 v11, s8, v11
	global_load_dwordx4 v[112:115], v[4:5], off
	global_load_dwordx4 v[116:119], v[6:7], off
	global_load_dwordx4 v[120:123], v[0:1], off
	global_load_dwordx4 v[124:127], v[4:5], off offset:16
	global_load_dwordx4 v[128:131], v[6:7], off offset:16
	global_load_dwordx4 v[132:135], v[0:1], off offset:16
	v_lshlrev_b32_e32 v3, 16, v163
	v_mul_f32_e32 v3, 0xbfb8aa3b, v3
	v_min_f32_e32 v3, 0x42fc0000, v3
	v_exp_f32_e32 v3, v3
	v_readlane_b32 s10, v254, 4
	v_readlane_b32 s11, v254, 5
	v_add_f32_e32 v3, 1.0, v3
	v_rcp_f32_e32 v3, v3
	s_nop 0
	v_div_scale_f32 v8, s[6:7], v32, v32, v3
	v_rcp_f32_e32 v9, v8
	v_div_scale_f32 v33, vcc, v3, v32, v3
	s_mov_b64 s[6:7], 0
	v_fma_f32 v48, -v8, v9, 1.0
	v_fmac_f32_e32 v9, v48, v9
	v_mul_f32_e32 v48, v33, v9
	v_fma_f32 v49, -v8, v48, v33
	v_fmac_f32_e32 v48, v49, v9
	v_fma_f32 v8, -v8, v48, v33
	v_div_fmas_f32 v8, v8, v9, v48
	v_div_fixup_f32 v8, v8, v32, v3
	s_waitcnt vmcnt(6)
	ds_write_b128 v10, v[248:251]
	s_waitcnt vmcnt(3)
	v_permlane32_swap_b32 v112, v114
	v_permlane32_swap_b32 v113, v115
	v_permlane32_swap_b32 v116, v118
	v_permlane32_swap_b32 v117, v119
	v_permlane32_swap_b32 v120, v122
	v_permlane32_swap_b32 v121, v123
	ds_read2st64_b32 v[40:41], v137 offset1:1
	ds_read2st64_b32 v[42:43], v137 offset0:2 offset1:3
	ds_read_b128 v[232:235], v11
	v_lshlrev_b32_e32 v3, 16, v112
	v_and_b32_e32 v9, 0xffff0000, v112
	v_lshlrev_b32_e32 v38, 16, v113
	v_and_b32_e32 v39, 0xffff0000, v113
	v_mul_f32_e32 v3, 0xbfb8aa3b, v3
	v_mul_f32_e32 v9, 0xbfb8aa3b, v9
	v_mul_f32_e32 v38, 0xbfb8aa3b, v38
	v_mul_f32_e32 v39, 0xbfb8aa3b, v39
	v_min_f32_e32 v3, 0x42fc0000, v3
	v_min_f32_e32 v9, 0x42fc0000, v9
	v_min_f32_e32 v38, 0x42fc0000, v38
	v_min_f32_e32 v39, 0x42fc0000, v39
	v_exp_f32_e32 v3, v3
	v_exp_f32_e32 v9, v9
	v_exp_f32_e32 v38, v38
	v_exp_f32_e32 v39, v39
	v_add_f32_e32 v3, 1.0, v3
	v_add_f32_e32 v9, 1.0, v9
	v_add_f32_e32 v50, 1.0, v38
	v_add_f32_e32 v51, 1.0, v39
	v_rcp_f32_e32 v38, v3
	v_rcp_f32_e32 v39, v9
	v_rcp_f32_e32 v50, v50
	v_rcp_f32_e32 v51, v51
	v_lshlrev_b32_e32 v48, 16, v116
	v_and_b32_e32 v49, 0xffff0000, v116
	v_lshlrev_b32_e32 v36, 16, v117
	v_and_b32_e32 v37, 0xffff0000, v117
	v_lshlrev_b32_e32 v44, 16, v120
	v_and_b32_e32 v45, 0xffff0000, v120
	v_lshlrev_b32_e32 v46, 16, v121
	v_and_b32_e32 v47, 0xffff0000, v121
	s_waitcnt lgkmcnt(0)
	v_pk_fma_f32 v[34:35], v[8:9], v[64:65], v[40:41] op_sel_hi:[0,1,1]
	v_pk_fma_f32 v[40:41], v[8:9], v[66:67], v[42:43] op_sel_hi:[0,1,1]
	v_pk_fma_f32 v[232:233], v[232:233], v[48:49], v[44:45]
	v_pk_fma_f32 v[234:235], v[234:235], v[36:37], v[46:47]
	v_pk_fma_f32 v[232:233], v[34:35], v[38:39], v[232:233]
	v_pk_fma_f32 v[234:235], v[40:41], v[50:51], v[234:235]
	v_cvt_pk_bf16_f32 v248, v232, v233
	v_cvt_pk_bf16_f32 v249, v234, v235
	ds_read2st64_b32 v[40:41], v137 offset0:16 offset1:17
	ds_read2st64_b32 v[42:43], v137 offset0:18 offset1:19
	ds_read_b128 v[236:239], v11 offset:128
	v_lshlrev_b32_e32 v3, 16, v114
	v_and_b32_e32 v9, 0xffff0000, v114
	v_lshlrev_b32_e32 v38, 16, v115
	v_and_b32_e32 v39, 0xffff0000, v115
	v_mul_f32_e32 v3, 0xbfb8aa3b, v3
	v_mul_f32_e32 v9, 0xbfb8aa3b, v9
	v_mul_f32_e32 v38, 0xbfb8aa3b, v38
	v_mul_f32_e32 v39, 0xbfb8aa3b, v39
	v_min_f32_e32 v3, 0x42fc0000, v3
	v_min_f32_e32 v9, 0x42fc0000, v9
	v_min_f32_e32 v38, 0x42fc0000, v38
	v_min_f32_e32 v39, 0x42fc0000, v39
	v_exp_f32_e32 v3, v3
	v_exp_f32_e32 v9, v9
	v_exp_f32_e32 v38, v38
	v_exp_f32_e32 v39, v39
	v_add_f32_e32 v3, 1.0, v3
	v_add_f32_e32 v9, 1.0, v9
	v_add_f32_e32 v50, 1.0, v38
	v_add_f32_e32 v51, 1.0, v39
	v_rcp_f32_e32 v38, v3
	v_rcp_f32_e32 v39, v9
	v_rcp_f32_e32 v50, v50
	v_rcp_f32_e32 v51, v51
	v_lshlrev_b32_e32 v48, 16, v118
	v_and_b32_e32 v49, 0xffff0000, v118
	v_lshlrev_b32_e32 v36, 16, v119
	v_and_b32_e32 v37, 0xffff0000, v119
	v_lshlrev_b32_e32 v44, 16, v122
	v_and_b32_e32 v45, 0xffff0000, v122
	v_lshlrev_b32_e32 v46, 16, v123
	v_and_b32_e32 v47, 0xffff0000, v123
	s_waitcnt lgkmcnt(0)
	v_pk_fma_f32 v[34:35], v[8:9], v[16:17], v[40:41] op_sel_hi:[0,1,1]
	v_pk_fma_f32 v[40:41], v[8:9], v[18:19], v[42:43] op_sel_hi:[0,1,1]
	v_pk_fma_f32 v[236:237], v[236:237], v[48:49], v[44:45]
	v_pk_fma_f32 v[238:239], v[238:239], v[36:37], v[46:47]
	v_pk_fma_f32 v[236:237], v[34:35], v[38:39], v[236:237]
	v_pk_fma_f32 v[238:239], v[40:41], v[50:51], v[238:239]
	v_cvt_pk_bf16_f32 v250, v236, v237
	v_cvt_pk_bf16_f32 v251, v238, v239
	s_nop 1
	v_permlane32_swap_b32 v248, v250
	v_permlane32_swap_b32 v249, v251
	global_store_dwordx4 v[0:1], v[248:251], off
	global_load_dwordx4 v[112:115], v[4:5], off offset:32
	global_load_dwordx4 v[116:119], v[6:7], off offset:32
	global_load_dwordx4 v[120:123], v[0:1], off offset:32
	s_waitcnt vmcnt(4)
; DI unsigned pk2(float lo, float hi) { const f32x2_t v = {lo, hi}; const bf16x2_t b = __builtin_convertvector(v, bf16x2_t); return __builtin_bit_cast(unsigned, b); }
; DI float sigmoidf_(float x) { return __builtin_amdgcn_rcpf(1.f + __builtin_amdgcn_exp2f(fminf(-x * LOG2E, 126.f))); }
; template <int DV>
; DI void attn_unit(const int wv, const Args& A, LAS unsigned char* lds, int b, int g, int qb, int dry) {
;     ...
;         bf16* Yb = (bf16*)A.out; const bf16* GMA = (const bf16*)(ws + WS_GMA);
; #pragma unroll
;         for (int mt = 0; mt < 2; ++mt)
; #pragma unroll
;             for (int v = 0; v < 4; ++v) {
;                 const size_t idx = tokrow * DM + head * 64 + mt * 32 + 8 * v + 4 * c.h;
;                 const u32x2 yr = *(const u32x2*)(Yb + idx), gm = *(const u32x2*)(GMA + idx), ct = *(const u32x2*)((const bf16*)(ws + WS_CT) + idx);
;                 const f32x4 cr = *(const f32x4*)((const float*)(ws + WS_CARRY) + ((size_t)b * 64 + (c.t >> 7)) * DM + head * 64 + mt * 32 + 8 * v + 4 * c.h);
;                 const float o0 = bflo(yr.x) + bflo(ct.x) * cr[0] + sigmoidf_(bflo(gm.x)) * O[mt][4 * v], o1 = bfhi(yr.x) + bfhi(ct.x) * cr[1] + sigmoidf_(bfhi(gm.x)) * O[mt][4 * v + 1];
;                 const float o2 = bflo(yr.y) + bflo(ct.y) * cr[2] + sigmoidf_(bflo(gm.y)) * O[mt][4 * v + 2], o3 = bfhi(yr.y) + bfhi(ct.y) * cr[3] + sigmoidf_(bfhi(gm.y)) * O[mt][4 * v + 3];
;                 *(u32x2*)(((dry & 1) ? (bf16*)(ws + 832 * MiB) : Yb) + idx) = (u32x2){pk2(o0, o1), pk2(o2, o3)};
;             }
	v_permlane32_swap_b32 v124, v126
	v_permlane32_swap_b32 v125, v127
	v_permlane32_swap_b32 v128, v130
	v_permlane32_swap_b32 v129, v131
	v_permlane32_swap_b32 v132, v134
	v_permlane32_swap_b32 v133, v135
	ds_read2st64_b32 v[40:41], v137 offset0:4 offset1:5
	ds_read2st64_b32 v[42:43], v137 offset0:6 offset1:7
	ds_read_b128 v[240:243], v11 offset:32
	v_lshlrev_b32_e32 v3, 16, v124
	v_and_b32_e32 v9, 0xffff0000, v124
	v_lshlrev_b32_e32 v38, 16, v125
	v_and_b32_e32 v39, 0xffff0000, v125
	v_mul_f32_e32 v3, 0xbfb8aa3b, v3
	v_mul_f32_e32 v9, 0xbfb8aa3b, v9
	v_mul_f32_e32 v38, 0xbfb8aa3b, v38
	v_mul_f32_e32 v39, 0xbfb8aa3b, v39
	v_min_f32_e32 v3, 0x42fc0000, v3
	v_min_f32_e32 v9, 0x42fc0000, v9
	v_min_f32_e32 v38, 0x42fc0000, v38
	v_min_f32_e32 v39, 0x42fc0000, v39
	v_exp_f32_e32 v3, v3
	v_exp_f32_e32 v9, v9
	v_exp_f32_e32 v38, v38
	v_exp_f32_e32 v39, v39
	v_add_f32_e32 v3, 1.0, v3
	v_add_f32_e32 v9, 1.0, v9
	v_add_f32_e32 v50, 1.0, v38
	v_add_f32_e32 v51, 1.0, v39
	v_rcp_f32_e32 v38, v3
	v_rcp_f32_e32 v39, v9
	v_rcp_f32_e32 v50, v50
	v_rcp_f32_e32 v51, v51
	v_lshlrev_b32_e32 v48, 16, v128
	v_and_b32_e32 v49, 0xffff0000, v128
	v_lshlrev_b32_e32 v36, 16, v129
	v_and_b32_e32 v37, 0xffff0000, v129
	v_lshlrev_b32_e32 v44, 16, v132
	v_and_b32_e32 v45, 0xffff0000, v132
	v_lshlrev_b32_e32 v46, 16, v133
	v_and_b32_e32 v47, 0xffff0000, v133
	s_waitcnt lgkmcnt(0)
	v_pk_fma_f32 v[34:35], v[8:9], v[68:69], v[40:41] op_sel_hi:[0,1,1]
	v_pk_fma_f32 v[40:41], v[8:9], v[70:71], v[42:43] op_sel_hi:[0,1,1]
	v_pk_fma_f32 v[240:241], v[240:241], v[48:49], v[44:45]
	v_pk_fma_f32 v[242:243], v[242:243], v[36:37], v[46:47]
	v_pk_fma_f32 v[240:241], v[34:35], v[38:39], v[240:241]
	v_pk_fma_f32 v[242:243], v[40:41], v[50:51], v[242:243]
	v_cvt_pk_bf16_f32 v248, v240, v241
	v_cvt_pk_bf16_f32 v249, v242, v243
	ds_read2st64_b32 v[40:41], v137 offset0:20 offset1:21
	ds_read2st64_b32 v[42:43], v137 offset0:22 offset1:23
	ds_read_b128 v[244:247], v11 offset:160
	v_lshlrev_b32_e32 v3, 16, v126
	v_and_b32_e32 v9, 0xffff0000, v126
	v_lshlrev_b32_e32 v38, 16, v127
	v_and_b32_e32 v39, 0xffff0000, v127
	v_mul_f32_e32 v3, 0xbfb8aa3b, v3
	v_mul_f32_e32 v9, 0xbfb8aa3b, v9
	v_mul_f32_e32 v38, 0xbfb8aa3b, v38
	v_mul_f32_e32 v39, 0xbfb8aa3b, v39
	v_min_f32_e32 v3, 0x42fc0000, v3
	v_min_f32_e32 v9, 0x42fc0000, v9
	v_min_f32_e32 v38, 0x42fc0000, v38
	v_min_f32_e32 v39, 0x42fc0000, v39
	v_exp_f32_e32 v3, v3
	v_exp_f32_e32 v9, v9
	v_exp_f32_e32 v38, v38
	v_exp_f32_e32 v39, v39
	v_add_f32_e32 v3, 1.0, v3
	v_add_f32_e32 v9, 1.0, v9
	v_add_f32_e32 v50, 1.0, v38
	v_add_f32_e32 v51, 1.0, v39
	v_rcp_f32_e32 v38, v3
	v_rcp_f32_e32 v39, v9
	v_rcp_f32_e32 v50, v50
	v_rcp_f32_e32 v51, v51
	v_lshlrev_b32_e32 v48, 16, v130
	v_and_b32_e32 v49, 0xffff0000, v130
	v_lshlrev_b32_e32 v36, 16, v131
	v_and_b32_e32 v37, 0xffff0000, v131
	v_lshlrev_b32_e32 v44, 16, v134
	v_and_b32_e32 v45, 0xffff0000, v134
	v_lshlrev_b32_e32 v46, 16, v135
	v_and_b32_e32 v47, 0xffff0000, v135
	s_waitcnt lgkmcnt(0)
	v_pk_fma_f32 v[34:35], v[8:9], v[20:21], v[40:41] op_sel_hi:[0,1,1]
	v_pk_fma_f32 v[40:41], v[8:9], v[22:23], v[42:43] op_sel_hi:[0,1,1]
	v_pk_fma_f32 v[244:245], v[244:245], v[48:49], v[44:45]
	v_pk_fma_f32 v[246:247], v[246:247], v[36:37], v[46:47]
	v_pk_fma_f32 v[244:245], v[34:35], v[38:39], v[244:245]
	v_pk_fma_f32 v[246:247], v[40:41], v[50:51], v[246:247]
	v_cvt_pk_bf16_f32 v250, v244, v245
	v_cvt_pk_bf16_f32 v251, v246, v247
	s_nop 1
	v_permlane32_swap_b32 v248, v250
	v_permlane32_swap_b32 v249, v251
	global_store_dwordx4 v[0:1], v[248:251], off offset:16
	global_load_dwordx4 v[124:127], v[4:5], off offset:48
	global_load_dwordx4 v[128:131], v[6:7], off offset:48
	global_load_dwordx4 v[132:135], v[0:1], off offset:48
	s_waitcnt vmcnt(4)
	v_permlane32_swap_b32 v112, v114
	v_permlane32_swap_b32 v113, v115
	v_permlane32_swap_b32 v116, v118
	v_permlane32_swap_b32 v117, v119
	v_permlane32_swap_b32 v120, v122
	v_permlane32_swap_b32 v121, v123
	ds_read2st64_b32 v[40:41], v137 offset0:8 offset1:9
	ds_read2st64_b32 v[42:43], v137 offset0:10 offset1:11
	ds_read_b128 v[232:235], v11 offset:64
	v_lshlrev_b32_e32 v3, 16, v112
	v_and_b32_e32 v9, 0xffff0000, v112
	v_lshlrev_b32_e32 v38, 16, v113
	v_and_b32_e32 v39, 0xffff0000, v113
	v_mul_f32_e32 v3, 0xbfb8aa3b, v3
	v_mul_f32_e32 v9, 0xbfb8aa3b, v9
	v_mul_f32_e32 v38, 0xbfb8aa3b, v38
	v_mul_f32_e32 v39, 0xbfb8aa3b, v39
	v_min_f32_e32 v3, 0x42fc0000, v3
	v_min_f32_e32 v9, 0x42fc0000, v9
	v_min_f32_e32 v38, 0x42fc0000, v38
	v_min_f32_e32 v39, 0x42fc0000, v39
	v_exp_f32_e32 v3, v3
	v_exp_f32_e32 v9, v9
	v_exp_f32_e32 v38, v38
	v_exp_f32_e32 v39, v39
	v_add_f32_e32 v3, 1.0, v3
	v_add_f32_e32 v9, 1.0, v9
	v_add_f32_e32 v50, 1.0, v38
	v_add_f32_e32 v51, 1.0, v39
	v_rcp_f32_e32 v38, v3
	v_rcp_f32_e32 v39, v9
	v_rcp_f32_e32 v50, v50
	v_rcp_f32_e32 v51, v51
	v_lshlrev_b32_e32 v48, 16, v116
	v_and_b32_e32 v49, 0xffff0000, v116
	v_lshlrev_b32_e32 v36, 16, v117
	v_and_b32_e32 v37, 0xffff0000, v117
	v_lshlrev_b32_e32 v44, 16, v120
	v_and_b32_e32 v45, 0xffff0000, v120
	v_lshlrev_b32_e32 v46, 16, v121
	v_and_b32_e32 v47, 0xffff0000, v121
	s_waitcnt lgkmcnt(0)
; DI unsigned pk2(float lo, float hi) { const f32x2_t v = {lo, hi}; const bf16x2_t b = __builtin_convertvector(v, bf16x2_t); return __builtin_bit_cast(unsigned, b); }
; DI float sigmoidf_(float x) { return __builtin_amdgcn_rcpf(1.f + __builtin_amdgcn_exp2f(fminf(-x * LOG2E, 126.f))); }
; template <int DV>
; DI void attn_unit(const int wv, const Args& A, LAS unsigned char* lds, int b, int g, int qb, int dry) {
;     ...
;         bf16* Yb = (bf16*)A.out; const bf16* GMA = (const bf16*)(ws + WS_GMA);
; #pragma unroll
;         for (int mt = 0; mt < 2; ++mt)
; #pragma unroll
;             for (int v = 0; v < 4; ++v) {
;                 const size_t idx = tokrow * DM + head * 64 + mt * 32 + 8 * v + 4 * c.h;
;                 const u32x2 yr = *(const u32x2*)(Yb + idx), gm = *(const u32x2*)(GMA + idx), ct = *(const u32x2*)((const bf16*)(ws + WS_CT) + idx);
;                 const f32x4 cr = *(const f32x4*)((const float*)(ws + WS_CARRY) + ((size_t)b * 64 + (c.t >> 7)) * DM + head * 64 + mt * 32 + 8 * v + 4 * c.h);
;                 const float o0 = bflo(yr.x) + bflo(ct.x) * cr[0] + sigmoidf_(bflo(gm.x)) * O[mt][4 * v], o1 = bfhi(yr.x) + bfhi(ct.x) * cr[1] + sigmoidf_(bfhi(gm.x)) * O[mt][4 * v + 1];
;                 const float o2 = bflo(yr.y) + bflo(ct.y) * cr[2] + sigmoidf_(bflo(gm.y)) * O[mt][4 * v + 2], o3 = bfhi(yr.y) + bfhi(ct.y) * cr[3] + sigmoidf_(bfhi(gm.y)) * O[mt][4 * v + 3];
;                 *(u32x2*)(((dry & 1) ? (bf16*)(ws + 832 * MiB) : Yb) + idx) = (u32x2){pk2(o0, o1), pk2(o2, o3)};
;             }
	v_pk_fma_f32 v[34:35], v[8:9], v[72:73], v[40:41] op_sel_hi:[0,1,1]
	v_pk_fma_f32 v[40:41], v[8:9], v[74:75], v[42:43] op_sel_hi:[0,1,1]
	v_pk_fma_f32 v[232:233], v[232:233], v[48:49], v[44:45]
	v_pk_fma_f32 v[234:235], v[234:235], v[36:37], v[46:47]
	v_pk_fma_f32 v[232:233], v[34:35], v[38:39], v[232:233]
	v_pk_fma_f32 v[234:235], v[40:41], v[50:51], v[234:235]
	v_cvt_pk_bf16_f32 v248, v232, v233
	v_cvt_pk_bf16_f32 v249, v234, v235
	ds_read2st64_b32 v[40:41], v137 offset0:24 offset1:25
	ds_read2st64_b32 v[42:43], v137 offset0:26 offset1:27
	ds_read_b128 v[236:239], v11 offset:192
	v_lshlrev_b32_e32 v3, 16, v114
	v_and_b32_e32 v9, 0xffff0000, v114
	v_lshlrev_b32_e32 v38, 16, v115
	v_and_b32_e32 v39, 0xffff0000, v115
	v_mul_f32_e32 v3, 0xbfb8aa3b, v3
	v_mul_f32_e32 v9, 0xbfb8aa3b, v9
	v_mul_f32_e32 v38, 0xbfb8aa3b, v38
	v_mul_f32_e32 v39, 0xbfb8aa3b, v39
	v_min_f32_e32 v3, 0x42fc0000, v3
	v_min_f32_e32 v9, 0x42fc0000, v9
	v_min_f32_e32 v38, 0x42fc0000, v38
	v_min_f32_e32 v39, 0x42fc0000, v39
	v_exp_f32_e32 v3, v3
	v_exp_f32_e32 v9, v9
	v_exp_f32_e32 v38, v38
	v_exp_f32_e32 v39, v39
	v_add_f32_e32 v3, 1.0, v3
	v_add_f32_e32 v9, 1.0, v9
	v_add_f32_e32 v50, 1.0, v38
	v_add_f32_e32 v51, 1.0, v39
	v_rcp_f32_e32 v38, v3
	v_rcp_f32_e32 v39, v9
	v_rcp_f32_e32 v50, v50
	v_rcp_f32_e32 v51, v51
	v_lshlrev_b32_e32 v48, 16, v118
	v_and_b32_e32 v49, 0xffff0000, v118
	v_lshlrev_b32_e32 v36, 16, v119
	v_and_b32_e32 v37, 0xffff0000, v119
	v_lshlrev_b32_e32 v44, 16, v122
	v_and_b32_e32 v45, 0xffff0000, v122
	v_lshlrev_b32_e32 v46, 16, v123
	v_and_b32_e32 v47, 0xffff0000, v123
	s_waitcnt lgkmcnt(0)
	v_pk_fma_f32 v[34:35], v[8:9], v[24:25], v[40:41] op_sel_hi:[0,1,1]
	v_pk_fma_f32 v[40:41], v[8:9], v[26:27], v[42:43] op_sel_hi:[0,1,1]
	v_pk_fma_f32 v[236:237], v[236:237], v[48:49], v[44:45]
	v_pk_fma_f32 v[238:239], v[238:239], v[36:37], v[46:47]
	v_pk_fma_f32 v[236:237], v[34:35], v[38:39], v[236:237]
	v_pk_fma_f32 v[238:239], v[40:41], v[50:51], v[238:239]
	v_cvt_pk_bf16_f32 v250, v236, v237
	v_cvt_pk_bf16_f32 v251, v238, v239
	s_nop 1
	v_permlane32_swap_b32 v248, v250
	v_permlane32_swap_b32 v249, v251
	global_store_dwordx4 v[0:1], v[248:251], off offset:32
	s_waitcnt vmcnt(1)
	v_permlane32_swap_b32 v124, v126
	v_permlane32_swap_b32 v125, v127
	v_permlane32_swap_b32 v128, v130
	v_permlane32_swap_b32 v129, v131
	v_permlane32_swap_b32 v132, v134
	v_permlane32_swap_b32 v133, v135
	ds_read2st64_b32 v[40:41], v137 offset0:12 offset1:13
	ds_read2st64_b32 v[42:43], v137 offset0:14 offset1:15
	ds_read_b128 v[240:243], v11 offset:96
	v_lshlrev_b32_e32 v3, 16, v124
	v_and_b32_e32 v9, 0xffff0000, v124
	v_lshlrev_b32_e32 v38, 16, v125
	v_and_b32_e32 v39, 0xffff0000, v125
	v_mul_f32_e32 v3, 0xbfb8aa3b, v3
	v_mul_f32_e32 v9, 0xbfb8aa3b, v9
	v_mul_f32_e32 v38, 0xbfb8aa3b, v38
	v_mul_f32_e32 v39, 0xbfb8aa3b, v39
	v_min_f32_e32 v3, 0x42fc0000, v3
	v_min_f32_e32 v9, 0x42fc0000, v9
	v_min_f32_e32 v38, 0x42fc0000, v38
	v_min_f32_e32 v39, 0x42fc0000, v39
	v_exp_f32_e32 v3, v3
	v_exp_f32_e32 v9, v9
	v_exp_f32_e32 v38, v38
	v_exp_f32_e32 v39, v39
	v_add_f32_e32 v3, 1.0, v3
	v_add_f32_e32 v9, 1.0, v9
	v_add_f32_e32 v50, 1.0, v38
	v_add_f32_e32 v51, 1.0, v39
	v_rcp_f32_e32 v38, v3
	v_rcp_f32_e32 v39, v9
	v_rcp_f32_e32 v50, v50
	v_rcp_f32_e32 v51, v51
	v_lshlrev_b32_e32 v48, 16, v128
	v_and_b32_e32 v49, 0xffff0000, v128
	v_lshlrev_b32_e32 v36, 16, v129
	v_and_b32_e32 v37, 0xffff0000, v129
	v_lshlrev_b32_e32 v44, 16, v132
	v_and_b32_e32 v45, 0xffff0000, v132
	v_lshlrev_b32_e32 v46, 16, v133
	v_and_b32_e32 v47, 0xffff0000, v133
	s_waitcnt lgkmcnt(0)
	v_pk_fma_f32 v[34:35], v[8:9], v[76:77], v[40:41] op_sel_hi:[0,1,1]
	v_pk_fma_f32 v[40:41], v[8:9], v[78:79], v[42:43] op_sel_hi:[0,1,1]
	v_pk_fma_f32 v[240:241], v[240:241], v[48:49], v[44:45]
	v_pk_fma_f32 v[242:243], v[242:243], v[36:37], v[46:47]
	v_pk_fma_f32 v[240:241], v[34:35], v[38:39], v[240:241]
	v_pk_fma_f32 v[242:243], v[40:41], v[50:51], v[242:243]
	v_cvt_pk_bf16_f32 v248, v240, v241
	v_cvt_pk_bf16_f32 v249, v242, v243
	ds_read2st64_b32 v[40:41], v137 offset0:28 offset1:29
	ds_read2st64_b32 v[42:43], v137 offset0:30 offset1:31
	ds_read_b128 v[244:247], v11 offset:224
	v_lshlrev_b32_e32 v3, 16, v126
	v_and_b32_e32 v9, 0xffff0000, v126
	v_lshlrev_b32_e32 v38, 16, v127
	v_and_b32_e32 v39, 0xffff0000, v127
	v_mul_f32_e32 v3, 0xbfb8aa3b, v3
	v_mul_f32_e32 v9, 0xbfb8aa3b, v9
	v_mul_f32_e32 v38, 0xbfb8aa3b, v38
	v_mul_f32_e32 v39, 0xbfb8aa3b, v39
	v_min_f32_e32 v3, 0x42fc0000, v3
	v_min_f32_e32 v9, 0x42fc0000, v9
	v_min_f32_e32 v38, 0x42fc0000, v38
	v_min_f32_e32 v39, 0x42fc0000, v39
	v_exp_f32_e32 v3, v3
	v_exp_f32_e32 v9, v9
	v_exp_f32_e32 v38, v38
	v_exp_f32_e32 v39, v39
	v_add_f32_e32 v3, 1.0, v3
	v_add_f32_e32 v9, 1.0, v9
	v_add_f32_e32 v50, 1.0, v38
	v_add_f32_e32 v51, 1.0, v39
	v_rcp_f32_e32 v38, v3
	v_rcp_f32_e32 v39, v9
	v_rcp_f32_e32 v50, v50
	v_rcp_f32_e32 v51, v51
	v_lshlrev_b32_e32 v48, 16, v130
	v_and_b32_e32 v49, 0xffff0000, v130
	v_lshlrev_b32_e32 v36, 16, v131
	v_and_b32_e32 v37, 0xffff0000, v131
	v_lshlrev_b32_e32 v44, 16, v134
	v_and_b32_e32 v45, 0xffff0000, v134
	v_lshlrev_b32_e32 v46, 16, v135
	v_and_b32_e32 v47, 0xffff0000, v135
	s_waitcnt lgkmcnt(0)
	v_pk_fma_f32 v[34:35], v[8:9], v[28:29], v[40:41] op_sel_hi:[0,1,1]
	v_pk_fma_f32 v[40:41], v[8:9], v[30:31], v[42:43] op_sel_hi:[0,1,1]
	v_pk_fma_f32 v[244:245], v[244:245], v[48:49], v[44:45]
	v_pk_fma_f32 v[246:247], v[246:247], v[36:37], v[46:47]
	v_pk_fma_f32 v[244:245], v[34:35], v[38:39], v[244:245]
	v_pk_fma_f32 v[246:247], v[40:41], v[50:51], v[246:247]
	v_cvt_pk_bf16_f32 v250, v244, v245
	v_cvt_pk_bf16_f32 v251, v246, v247
	s_nop 1
	v_permlane32_swap_b32 v248, v250
	v_permlane32_swap_b32 v249, v251
	global_store_dwordx4 v[0:1], v[248:251], off offset:48
